# combo31: combo23 + section 7.11 back-edge rotation of the P4/P5/P6 GEMM K-loops (counter updates and next-iteration scalar selects moved in front of the loop-back barrier)
# speedup vs baseline: 1.0012x; 1.0012x over previous
; #define PG8_STAGE(bufoff, gbase, voff) do { _Pragma("unroll") for (int _i = 0; _i < 2; ++_i) \
;         __builtin_amdgcn_global_load_lds((const unsigned*)((const char*)(gbase) + (voff)[_i]), (PG8_LAS unsigned*)(lds + (bufoff) + ldsw + _i * 8192), 16, 0, 0); } while (0)
; #define PG8_LDA(dst, b, h) do { _Pragma("unroll") for (int m = 0; m < 4; ++m) _Pragma("unroll") for (int k = 0; k < 2; ++k) dst[m][k] = *(const PG8_LAS bf16x8*)(lds + PG8_SA(b, h) + aoff + m * 2048 + k * 1024); } while (0)
; #define PG8_LDB(dst, b, h) do { _Pragma("unroll") for (int n = 0; n < 2; ++n) _Pragma("unroll") for (int k = 0; k < 2; ++k) dst[n][k] = *(const PG8_LAS bf16x8*)(lds + PG8_SB(b, h) + boff + n * 2048 + k * 1024); } while (0)
; #define PG8_MMA(ai, bj, At, Bt) do { __builtin_amdgcn_s_setprio(1); _Pragma("unroll") for (int m = 0; m < 4; ++m) _Pragma("unroll") for (int n = 0; n < 2; ++n) _Pragma("unroll") for (int k = 0; k < 2; ++k) \
;         acc[ai][bj][m][n] = __builtin_amdgcn_mfma_f32_16x16x32_bf16(Bt[n][k], At[m][k], acc[ai][bj][m][n], 0, 0, 0); __builtin_amdgcn_s_setprio(0); } while (0)
; #define PG8_WAIT_V(n) asm volatile("s_waitcnt vmcnt(" #n ")" ::: "memory")
; #define PG8_WAIT_L(n) asm volatile("s_waitcnt lgkmcnt(" #n ")" ::: "memory")
; #define PG8_BAR __builtin_amdgcn_s_barrier()
; #define PG8_SCHED __builtin_amdgcn_sched_barrier(0)
; template <class Epi, class Sched, bool ALIGN_EPI = false, bool SP2 = false>
; __device__ __forceinline__ void gemm_phase(PG8_LAS unsigned char* lds, const Gemm g, const Sched& S, const Epi& E) {
;     ...
;             PG8_LDB(B0, 0, 0); PG8_LDB(B1, 0, 1); PG8_SCHED; PG8_LDA(At, 0, 0); PG8_STAGE(PG8_SA(1, 1), a1 + hstep, voffA);
;             PG8_WAIT_V(8); PG8_WAIT_L(0); PG8_BAR; PG8_MMA(0, 0, At, B0); PG8_MMA(0, 1, At, B1); PG8_BAR; PG8_SCHED;
;             PG8_LDA(At, 0, 1); PG8_STAGE(PG8_SB(0, 0), b2, voffB); PG8_STAGE(PG8_SB(0, 1), b2 + hstep, voffB); PG8_STAGE(PG8_SA(0, 0), a2, voffA);
;             PG8_WAIT_V(8); PG8_WAIT_L(0); PG8_BAR; PG8_MMA(1, 0, At, B0); PG8_MMA(1, 1, At, B1); PG8_BAR; PG8_SCHED;
.Lkrot_945:
	v_add_u32_e32 v56, s49, v205
	v_add_u32_e32 v158, s52, v205
	ds_read_b128 v[40:43], v56
	ds_read_b128 v[44:47], v56 offset:1024
	ds_read_b128 v[52:55], v56 offset:2048
	ds_read_b128 v[56:59], v56 offset:3072
	ds_read_b128 v[144:147], v158
	ds_read_b128 v[162:165], v158 offset:1024
	ds_read_b128 v[166:169], v158 offset:2048
	ds_read_b128 v[170:173], v158 offset:3072
	v_lshl_add_u64 v[158:159], s[4:5], 0, v[154:155]
	s_add_i32 m0, s29, 0xc000
	ds_read_b128 v[174:177], v206
	ds_read_b128 v[178:181], v206 offset:1024
	ds_read_b128 v[182:185], v206 offset:2048
	ds_read_b128 v[186:189], v206 offset:3072
	ds_read_b128 v[194:197], v206 offset:4096
	ds_read_b128 v[208:211], v206 offset:5120
	ds_read_b128 v[212:215], v206 offset:6144
	ds_read_b128 v[216:219], v206 offset:7168
	global_load_lds_dwordx4 v[158:159], off
	v_lshl_add_u64 v[158:159], s[4:5], 0, v[156:157]
	s_add_i32 m0, s29, 0xe000
	s_nop 0
	global_load_lds_dwordx4 v[158:159], off
	s_waitcnt vmcnt(8)
	s_waitcnt lgkmcnt(0)
	s_barrier
	s_setprio 1
	s_waitcnt lgkmcnt(0)
	v_mfma_f32_16x16x32_bf16 v[140:143], v[40:43], v[174:177], v[140:143]
	v_mfma_f32_16x16x32_bf16 v[136:139], v[52:55], v[174:177], v[136:139]
	v_mfma_f32_16x16x32_bf16 v[124:127], v[40:43], v[182:185], v[124:127]
	v_mfma_f32_16x16x32_bf16 v[120:123], v[52:55], v[182:185], v[120:123]
	v_mfma_f32_16x16x32_bf16 v[108:111], v[40:43], v[194:197], v[108:111]
	v_mfma_f32_16x16x32_bf16 v[104:107], v[52:55], v[194:197], v[104:107]
	v_mfma_f32_16x16x32_bf16 v[92:95], v[40:43], v[212:215], v[92:95]
	v_mfma_f32_16x16x32_bf16 v[88:91], v[52:55], v[212:215], v[88:91]
	v_mfma_f32_16x16x32_bf16 v[140:143], v[44:47], v[178:181], v[140:143]
	v_mfma_f32_16x16x32_bf16 v[136:139], v[56:59], v[178:181], v[136:139]
	v_mfma_f32_16x16x32_bf16 v[124:127], v[44:47], v[186:189], v[124:127]
	v_mfma_f32_16x16x32_bf16 v[120:123], v[56:59], v[186:189], v[120:123]
	v_mfma_f32_16x16x32_bf16 v[108:111], v[44:47], v[208:211], v[108:111]
	v_mfma_f32_16x16x32_bf16 v[104:107], v[56:59], v[208:211], v[104:107]
	v_mfma_f32_16x16x32_bf16 v[92:95], v[44:47], v[216:219], v[92:95]
	v_mfma_f32_16x16x32_bf16 v[88:91], v[56:59], v[216:219], v[88:91]
	s_setprio 0
	s_setprio 1
	v_mfma_f32_16x16x32_bf16 v[132:135], v[144:147], v[174:177], v[132:135]
	v_mfma_f32_16x16x32_bf16 v[128:131], v[166:169], v[174:177], v[128:131]
	v_mfma_f32_16x16x32_bf16 v[116:119], v[144:147], v[182:185], v[116:119]
	v_mfma_f32_16x16x32_bf16 v[112:115], v[166:169], v[182:185], v[112:115]
	v_mfma_f32_16x16x32_bf16 v[100:103], v[144:147], v[194:197], v[100:103]
	v_mfma_f32_16x16x32_bf16 v[96:99], v[166:169], v[194:197], v[96:99]
	v_mfma_f32_16x16x32_bf16 v[84:87], v[144:147], v[212:215], v[84:87]
	v_mfma_f32_16x16x32_bf16 v[80:83], v[166:169], v[212:215], v[80:83]
	v_mfma_f32_16x16x32_bf16 v[132:135], v[162:165], v[178:181], v[132:135]
	v_mfma_f32_16x16x32_bf16 v[128:131], v[170:173], v[178:181], v[128:131]
	v_mfma_f32_16x16x32_bf16 v[116:119], v[162:165], v[186:189], v[116:119]
	v_mfma_f32_16x16x32_bf16 v[112:115], v[170:173], v[186:189], v[112:115]
	v_mfma_f32_16x16x32_bf16 v[100:103], v[162:165], v[208:211], v[100:103]
	v_mfma_f32_16x16x32_bf16 v[96:99], v[170:173], v[208:211], v[96:99]
	v_mfma_f32_16x16x32_bf16 v[84:87], v[162:165], v[216:219], v[84:87]
	v_mfma_f32_16x16x32_bf16 v[80:83], v[170:173], v[216:219], v[80:83]
	s_setprio 0
	s_barrier
	s_add_i32 s49, s49, s28
	v_lshl_add_u64 v[158:159], s[6:7], 0, v[160:161]
	s_mov_b32 m0, s49
	ds_read_b128 v[174:177], v206 offset:16384
	ds_read_b128 v[178:181], v206 offset:17408
	ds_read_b128 v[182:185], v206 offset:18432
	ds_read_b128 v[186:189], v206 offset:19456
	ds_read_b128 v[194:197], v206 offset:20480
	ds_read_b128 v[208:211], v206 offset:21504
	ds_read_b128 v[212:215], v206 offset:22528
	ds_read_b128 v[216:219], v206 offset:23552
	global_load_lds_dwordx4 v[158:159], off
	s_add_i32 m0, s49, 0x2000
	s_add_u32 s50, s6, 0x40000
	v_lshl_add_u64 v[220:221], s[6:7], 0, v[148:149]
	s_addc_u32 s51, s7, 0
	s_add_i32 s49, s52, s28
	global_load_lds_dwordx4 v[220:221], off
	v_lshl_add_u64 v[222:223], s[50:51], 0, v[160:161]
	s_mov_b32 m0, s49
	v_lshl_add_u64 v[224:225], s[22:23], 0, v[150:151]
	global_load_lds_dwordx4 v[222:223], off
	v_lshl_add_u64 v[222:223], s[50:51], 0, v[148:149]
	s_add_i32 m0, s49, 0x2000
	s_nop 0
	global_load_lds_dwordx4 v[222:223], off
	v_lshl_add_u64 v[222:223], s[22:23], 0, v[152:153]
	s_mov_b32 m0, s29
	s_nop 0
	global_load_lds_dwordx4 v[222:223], off
	s_mov_b32 m0, s30
	s_nop 0
	global_load_lds_dwordx4 v[224:225], off
	s_waitcnt vmcnt(8)
	s_waitcnt lgkmcnt(0)
	s_barrier
; #define PG8_STAGE(bufoff, gbase, voff) do { _Pragma("unroll") for (int _i = 0; _i < 2; ++_i) \
;         __builtin_amdgcn_global_load_lds((const unsigned*)((const char*)(gbase) + (voff)[_i]), (PG8_LAS unsigned*)(lds + (bufoff) + ldsw + _i * 8192), 16, 0, 0); } while (0)
; #define PG8_LDA(dst, b, h) do { _Pragma("unroll") for (int m = 0; m < 4; ++m) _Pragma("unroll") for (int k = 0; k < 2; ++k) dst[m][k] = *(const PG8_LAS bf16x8*)(lds + PG8_SA(b, h) + aoff + m * 2048 + k * 1024); } while (0)
; #define PG8_LDB(dst, b, h) do { _Pragma("unroll") for (int n = 0; n < 2; ++n) _Pragma("unroll") for (int k = 0; k < 2; ++k) dst[n][k] = *(const PG8_LAS bf16x8*)(lds + PG8_SB(b, h) + boff + n * 2048 + k * 1024); } while (0)
; #define PG8_MMA(ai, bj, At, Bt) do { __builtin_amdgcn_s_setprio(1); _Pragma("unroll") for (int m = 0; m < 4; ++m) _Pragma("unroll") for (int n = 0; n < 2; ++n) _Pragma("unroll") for (int k = 0; k < 2; ++k) \
;         acc[ai][bj][m][n] = __builtin_amdgcn_mfma_f32_16x16x32_bf16(Bt[n][k], At[m][k], acc[ai][bj][m][n], 0, 0, 0); __builtin_amdgcn_s_setprio(0); } while (0)
; #define PG8_WAIT_V(n) asm volatile("s_waitcnt vmcnt(" #n ")" ::: "memory")
; #define PG8_WAIT_L(n) asm volatile("s_waitcnt lgkmcnt(" #n ")" ::: "memory")
; #define PG8_BAR __builtin_amdgcn_s_barrier()
; #define PG8_SCHED __builtin_amdgcn_sched_barrier(0)
; template <class Epi, class Sched, bool ALIGN_EPI = false, bool SP2 = false>
; __device__ __forceinline__ void gemm_phase(PG8_LAS unsigned char* lds, const Gemm g, const Sched& S, const Epi& E) {
;     ...
;             PG8_WAIT_V(8); PG8_WAIT_L(0); PG8_BAR; PG8_MMA(1, 0, At, B0); PG8_MMA(1, 1, At, B1); PG8_BAR; PG8_SCHED;
;             PG8_LDB(B0, 1, 0); PG8_LDB(B1, 1, 1); PG8_SCHED; PG8_LDA(At, 1, 0); PG8_STAGE(PG8_SA(0, 1), a2 + hstep, voffA);
;             PG8_WAIT_V(8); PG8_WAIT_L(0); PG8_BAR; PG8_MMA(0, 0, At, B0); PG8_MMA(0, 1, At, B1); PG8_BAR; PG8_SCHED;
	s_setprio 1
	s_waitcnt lgkmcnt(0)
	v_mfma_f32_16x16x32_bf16 v[76:79], v[40:43], v[174:177], v[76:79]
	v_mfma_f32_16x16x32_bf16 v[72:75], v[52:55], v[174:177], v[72:75]
	v_mfma_f32_16x16x32_bf16 v[60:63], v[40:43], v[182:185], v[60:63]
	v_mfma_f32_16x16x32_bf16 v[48:51], v[52:55], v[182:185], v[48:51]
	v_mfma_f32_16x16x32_bf16 v[28:31], v[40:43], v[194:197], v[28:31]
	v_mfma_f32_16x16x32_bf16 v[24:27], v[52:55], v[194:197], v[24:27]
	v_mfma_f32_16x16x32_bf16 v[12:15], v[40:43], v[212:215], v[12:15]
	v_mfma_f32_16x16x32_bf16 v[8:11], v[52:55], v[212:215], v[8:11]
	v_mfma_f32_16x16x32_bf16 v[76:79], v[44:47], v[178:181], v[76:79]
	v_mfma_f32_16x16x32_bf16 v[72:75], v[56:59], v[178:181], v[72:75]
	v_mfma_f32_16x16x32_bf16 v[60:63], v[44:47], v[186:189], v[60:63]
	v_mfma_f32_16x16x32_bf16 v[48:51], v[56:59], v[186:189], v[48:51]
	v_mfma_f32_16x16x32_bf16 v[28:31], v[44:47], v[208:211], v[28:31]
	v_mfma_f32_16x16x32_bf16 v[24:27], v[56:59], v[208:211], v[24:27]
	v_mfma_f32_16x16x32_bf16 v[12:15], v[44:47], v[216:219], v[12:15]
	v_mfma_f32_16x16x32_bf16 v[8:11], v[56:59], v[216:219], v[8:11]
	s_setprio 0
	s_setprio 1
	v_mfma_f32_16x16x32_bf16 v[36:39], v[144:147], v[182:185], v[36:39]
	v_mfma_f32_16x16x32_bf16 v[32:35], v[166:169], v[182:185], v[32:35]
	v_mfma_f32_16x16x32_bf16 v[20:23], v[144:147], v[194:197], v[20:23]
	v_mfma_f32_16x16x32_bf16 v[16:19], v[166:169], v[194:197], v[16:19]
	v_mfma_f32_16x16x32_bf16 v[4:7], v[144:147], v[212:215], v[4:7]
	v_mfma_f32_16x16x32_bf16 v[0:3], v[166:169], v[212:215], v[0:3]
	v_mfma_f32_16x16x32_bf16 v[40:43], v[144:147], v[174:177], v[68:71]
	v_mfma_f32_16x16x32_bf16 v[44:47], v[166:169], v[174:177], v[64:67]
	v_mfma_f32_16x16x32_bf16 v[36:39], v[162:165], v[186:189], v[36:39]
	v_mfma_f32_16x16x32_bf16 v[32:35], v[170:173], v[186:189], v[32:35]
	v_mfma_f32_16x16x32_bf16 v[20:23], v[162:165], v[208:211], v[20:23]
	v_mfma_f32_16x16x32_bf16 v[16:19], v[170:173], v[208:211], v[16:19]
	v_mfma_f32_16x16x32_bf16 v[4:7], v[162:165], v[216:219], v[4:7]
	v_mfma_f32_16x16x32_bf16 v[0:3], v[170:173], v[216:219], v[0:3]
	v_mfma_f32_16x16x32_bf16 v[40:43], v[162:165], v[178:181], v[40:43]
	v_mfma_f32_16x16x32_bf16 v[44:47], v[170:173], v[178:181], v[44:47]
	s_setprio 0
	s_barrier
	s_add_i32 s49, 0, 0x18000
	s_add_i32 s50, 0, 0x1c000
	v_add_u32_e32 v68, s49, v205
	v_add_u32_e32 v170, s50, v205
	ds_read_b128 v[52:55], v68
	ds_read_b128 v[56:59], v68 offset:1024
	ds_read_b128 v[64:67], v68 offset:2048
	ds_read_b128 v[68:71], v68 offset:3072
	ds_read_b128 v[144:147], v170
	ds_read_b128 v[162:165], v170 offset:1024
	ds_read_b128 v[166:169], v170 offset:2048
	ds_read_b128 v[170:173], v170 offset:3072
	s_add_u32 s22, s22, 0x40000
	s_addc_u32 s23, s23, 0
	s_mov_b32 m0, s31
	v_lshl_add_u64 v[226:227], s[22:23], 0, v[152:153]
	ds_read_b128 v[174:177], v206 offset:32768
	ds_read_b128 v[178:181], v206 offset:33792
	ds_read_b128 v[182:185], v206 offset:34816
	ds_read_b128 v[186:189], v206 offset:35840
	ds_read_b128 v[194:197], v206 offset:36864
	ds_read_b128 v[208:211], v206 offset:37888
	ds_read_b128 v[212:215], v206 offset:38912
	ds_read_b128 v[216:219], v206 offset:39936
	global_load_lds_dwordx4 v[226:227], off
	v_lshl_add_u64 v[226:227], s[22:23], 0, v[150:151]
	s_mov_b32 m0, s34
	s_nop 0
	global_load_lds_dwordx4 v[226:227], off
	s_waitcnt vmcnt(8)
	s_waitcnt lgkmcnt(0)
	s_barrier
	s_setprio 1
	s_waitcnt lgkmcnt(0)
	v_mfma_f32_16x16x32_bf16 v[140:143], v[52:55], v[174:177], v[140:143]
	v_mfma_f32_16x16x32_bf16 v[136:139], v[64:67], v[174:177], v[136:139]
	v_mfma_f32_16x16x32_bf16 v[124:127], v[52:55], v[182:185], v[124:127]
	v_mfma_f32_16x16x32_bf16 v[120:123], v[64:67], v[182:185], v[120:123]
	v_mfma_f32_16x16x32_bf16 v[108:111], v[52:55], v[194:197], v[108:111]
	v_mfma_f32_16x16x32_bf16 v[104:107], v[64:67], v[194:197], v[104:107]
	v_mfma_f32_16x16x32_bf16 v[92:95], v[52:55], v[212:215], v[92:95]
	v_mfma_f32_16x16x32_bf16 v[88:91], v[64:67], v[212:215], v[88:91]
	v_mfma_f32_16x16x32_bf16 v[140:143], v[56:59], v[178:181], v[140:143]
	v_mfma_f32_16x16x32_bf16 v[136:139], v[68:71], v[178:181], v[136:139]
	v_mfma_f32_16x16x32_bf16 v[124:127], v[56:59], v[186:189], v[124:127]
	v_mfma_f32_16x16x32_bf16 v[120:123], v[68:71], v[186:189], v[120:123]
	v_mfma_f32_16x16x32_bf16 v[108:111], v[56:59], v[208:211], v[108:111]
	v_mfma_f32_16x16x32_bf16 v[104:107], v[68:71], v[208:211], v[104:107]
	v_mfma_f32_16x16x32_bf16 v[92:95], v[56:59], v[216:219], v[92:95]
	v_mfma_f32_16x16x32_bf16 v[88:91], v[68:71], v[216:219], v[88:91]
	s_setprio 0
	s_setprio 1
	v_mfma_f32_16x16x32_bf16 v[132:135], v[144:147], v[174:177], v[132:135]
	v_mfma_f32_16x16x32_bf16 v[128:131], v[166:169], v[174:177], v[128:131]
	v_mfma_f32_16x16x32_bf16 v[116:119], v[144:147], v[182:185], v[116:119]
	v_mfma_f32_16x16x32_bf16 v[112:115], v[166:169], v[182:185], v[112:115]
	v_mfma_f32_16x16x32_bf16 v[100:103], v[144:147], v[194:197], v[100:103]
	v_mfma_f32_16x16x32_bf16 v[96:99], v[166:169], v[194:197], v[96:99]
	v_mfma_f32_16x16x32_bf16 v[84:87], v[144:147], v[212:215], v[84:87]
	v_mfma_f32_16x16x32_bf16 v[80:83], v[166:169], v[212:215], v[80:83]
	v_mfma_f32_16x16x32_bf16 v[132:135], v[162:165], v[178:181], v[132:135]
	v_mfma_f32_16x16x32_bf16 v[128:131], v[170:173], v[178:181], v[128:131]
	v_mfma_f32_16x16x32_bf16 v[116:119], v[162:165], v[186:189], v[116:119]
	v_mfma_f32_16x16x32_bf16 v[112:115], v[170:173], v[186:189], v[112:115]
	v_mfma_f32_16x16x32_bf16 v[100:103], v[162:165], v[208:211], v[100:103]
	v_mfma_f32_16x16x32_bf16 v[96:99], v[170:173], v[208:211], v[96:99]
	v_mfma_f32_16x16x32_bf16 v[84:87], v[162:165], v[216:219], v[84:87]
	v_mfma_f32_16x16x32_bf16 v[80:83], v[170:173], v[216:219], v[80:83]
	s_setprio 0
	s_barrier
; #define PG8_STAGE(bufoff, gbase, voff) do { _Pragma("unroll") for (int _i = 0; _i < 2; ++_i) \
;         __builtin_amdgcn_global_load_lds((const unsigned*)((const char*)(gbase) + (voff)[_i]), (PG8_LAS unsigned*)(lds + (bufoff) + ldsw + _i * 8192), 16, 0, 0); } while (0)
; #define PG8_LDA(dst, b, h) do { _Pragma("unroll") for (int m = 0; m < 4; ++m) _Pragma("unroll") for (int k = 0; k < 2; ++k) dst[m][k] = *(const PG8_LAS bf16x8*)(lds + PG8_SA(b, h) + aoff + m * 2048 + k * 1024); } while (0)
; #define PG8_MMA(ai, bj, At, Bt) do { __builtin_amdgcn_s_setprio(1); _Pragma("unroll") for (int m = 0; m < 4; ++m) _Pragma("unroll") for (int n = 0; n < 2; ++n) _Pragma("unroll") for (int k = 0; k < 2; ++k) \
;         acc[ai][bj][m][n] = __builtin_amdgcn_mfma_f32_16x16x32_bf16(Bt[n][k], At[m][k], acc[ai][bj][m][n], 0, 0, 0); __builtin_amdgcn_s_setprio(0); } while (0)
; #define PG8_WAIT_V(n) asm volatile("s_waitcnt vmcnt(" #n ")" ::: "memory")
; #define PG8_WAIT_L(n) asm volatile("s_waitcnt lgkmcnt(" #n ")" ::: "memory")
; #define PG8_BAR __builtin_amdgcn_s_barrier()
; #define PG8_SCHED __builtin_amdgcn_sched_barrier(0)
; template <class Epi, class Sched, bool ALIGN_EPI = false, bool SP2 = false>
; __device__ __forceinline__ void gemm_phase(PG8_LAS unsigned char* lds, const Gemm g, const Sched& S, const Epi& E) {
;     ...
;         for (int t = 0; t < nt; t += 2) {
;             const bool last = (t == nt - 2);
;             const char* a1 = cA + (size_t)(t + 1) * kstep;
;             const char* a2 = last ? nA : cA + (size_t)(t + 2) * kstep; const char* b2 = last ? nB : cB + (size_t)(t + 2) * kstep;
;             const char* a3 = a2 + kstep; const char* b3 = b2 + kstep;
;             if (last && has_next) S.a_ready(nxt);
;     ...
;             PG8_LDA(At, 1, 1); PG8_STAGE(PG8_SB(1, 0), b3, voffB); PG8_STAGE(PG8_SB(1, 1), b3 + hstep, voffB); PG8_STAGE(PG8_SA(1, 0), a3, voffA);
;             PG8_WAIT_V(8); PG8_WAIT_L(0); PG8_BAR; PG8_MMA(1, 0, At, B0); PG8_MMA(1, 1, At, B1); PG8_BAR; PG8_SCHED;
	s_add_i32 s22, s49, s28
	v_lshl_add_u64 v[158:159], v[158:159], 0, s[38:39]
	s_mov_b32 m0, s22
	ds_read_b128 v[174:177], v206 offset:49152
	ds_read_b128 v[178:181], v206 offset:50176
	ds_read_b128 v[182:185], v206 offset:51200
	ds_read_b128 v[186:189], v206 offset:52224
	ds_read_b128 v[194:197], v206 offset:53248
	ds_read_b128 v[208:211], v206 offset:54272
	ds_read_b128 v[212:215], v206 offset:55296
	ds_read_b128 v[216:219], v206 offset:56320
	global_load_lds_dwordx4 v[158:159], off
	s_add_i32 m0, s22, 0x2000
	s_add_u32 s6, s6, 0x40080
	v_lshl_add_u64 v[158:159], v[220:221], 0, s[38:39]
	s_addc_u32 s7, s7, 0
	s_add_i32 s22, s50, s28
	global_load_lds_dwordx4 v[158:159], off
	v_lshl_add_u64 v[158:159], s[6:7], 0, v[160:161]
	s_mov_b32 m0, s22
	s_nop 0
	global_load_lds_dwordx4 v[158:159], off
	v_lshl_add_u64 v[158:159], s[6:7], 0, v[148:149]
	s_add_i32 m0, s22, 0x2000
	s_nop 0
	global_load_lds_dwordx4 v[158:159], off
	v_lshl_add_u64 v[158:159], v[222:223], 0, s[38:39]
	s_mov_b32 m0, s41
	s_nop 0
	global_load_lds_dwordx4 v[158:159], off
	v_lshl_add_u64 v[158:159], v[224:225], 0, s[38:39]
	s_mov_b32 m0, s42
	s_nop 0
	global_load_lds_dwordx4 v[158:159], off
	s_waitcnt vmcnt(8)
	s_waitcnt lgkmcnt(0)
	s_barrier
	s_setprio 1
	s_waitcnt lgkmcnt(0)
	v_mfma_f32_16x16x32_bf16 v[76:79], v[52:55], v[174:177], v[76:79]
	v_mfma_f32_16x16x32_bf16 v[72:75], v[64:67], v[174:177], v[72:75]
	v_mfma_f32_16x16x32_bf16 v[60:63], v[52:55], v[182:185], v[60:63]
	v_mfma_f32_16x16x32_bf16 v[48:51], v[64:67], v[182:185], v[48:51]
	v_mfma_f32_16x16x32_bf16 v[28:31], v[52:55], v[194:197], v[28:31]
	v_mfma_f32_16x16x32_bf16 v[24:27], v[64:67], v[194:197], v[24:27]
	v_mfma_f32_16x16x32_bf16 v[12:15], v[52:55], v[212:215], v[12:15]
	v_mfma_f32_16x16x32_bf16 v[8:11], v[64:67], v[212:215], v[8:11]
	v_mfma_f32_16x16x32_bf16 v[76:79], v[56:59], v[178:181], v[76:79]
	v_mfma_f32_16x16x32_bf16 v[72:75], v[68:71], v[178:181], v[72:75]
	v_mfma_f32_16x16x32_bf16 v[60:63], v[56:59], v[186:189], v[60:63]
	v_mfma_f32_16x16x32_bf16 v[48:51], v[68:71], v[186:189], v[48:51]
	v_mfma_f32_16x16x32_bf16 v[28:31], v[56:59], v[208:211], v[28:31]
	v_mfma_f32_16x16x32_bf16 v[24:27], v[68:71], v[208:211], v[24:27]
	v_mfma_f32_16x16x32_bf16 v[12:15], v[56:59], v[216:219], v[12:15]
	v_mfma_f32_16x16x32_bf16 v[8:11], v[68:71], v[216:219], v[8:11]
	s_setprio 0
	s_setprio 1
	v_mfma_f32_16x16x32_bf16 v[40:43], v[144:147], v[174:177], v[40:43]
	v_mfma_f32_16x16x32_bf16 v[68:71], v[162:165], v[178:181], v[40:43]
	v_mfma_f32_16x16x32_bf16 v[40:43], v[166:169], v[174:177], v[44:47]
	v_mfma_f32_16x16x32_bf16 v[36:39], v[144:147], v[182:185], v[36:39]
	v_mfma_f32_16x16x32_bf16 v[32:35], v[166:169], v[182:185], v[32:35]
	v_mfma_f32_16x16x32_bf16 v[20:23], v[144:147], v[194:197], v[20:23]
	v_mfma_f32_16x16x32_bf16 v[16:19], v[166:169], v[194:197], v[16:19]
	v_mfma_f32_16x16x32_bf16 v[4:7], v[144:147], v[212:215], v[4:7]
	v_mfma_f32_16x16x32_bf16 v[0:3], v[166:169], v[212:215], v[0:3]
	v_mfma_f32_16x16x32_bf16 v[64:67], v[170:173], v[178:181], v[40:43]
	v_mfma_f32_16x16x32_bf16 v[36:39], v[162:165], v[186:189], v[36:39]
	v_mfma_f32_16x16x32_bf16 v[32:35], v[170:173], v[186:189], v[32:35]
	v_mfma_f32_16x16x32_bf16 v[20:23], v[162:165], v[208:211], v[20:23]
	v_mfma_f32_16x16x32_bf16 v[16:19], v[170:173], v[208:211], v[16:19]
	v_mfma_f32_16x16x32_bf16 v[4:7], v[162:165], v[216:219], v[4:7]
	v_mfma_f32_16x16x32_bf16 v[0:3], v[170:173], v[216:219], v[0:3]
	s_setprio 0
	s_add_i32 s48, s48, 2
	s_add_u32 s4, s4, 0x100
	s_addc_u32 s5, s5, 0
	s_add_u32 s46, s46, 0x100
	s_addc_u32 s47, s47, 0
	s_add_u32 s6, s4, 0xfffc0080
	s_addc_u32 s7, s5, -1
	s_add_i32 s49, 0, 0x10000
	s_cmp_eq_u32 s48, 12
	s_cselect_b32 s23, s15, s7
	s_cselect_b32 s22, s44, s6
	s_cselect_b32 s7, s17, s47
	s_cselect_b32 s6, s45, s46
	s_add_i32 s52, 0, 0x14000
	s_cmp_gt_u32 s48, 13
	s_barrier
	s_cbranch_scc0 .Lkrot_945
	s_and_b64 vcc, exec, s[12:13]
	s_cbranch_vccz .LBB0_948
	s_barrier

; #define PG8_STAGE(bufoff, gbase, voff) do { _Pragma("unroll") for (int _i = 0; _i < 2; ++_i) \
;         __builtin_amdgcn_global_load_lds((const unsigned*)((const char*)(gbase) + (voff)[_i]), (PG8_LAS unsigned*)(lds + (bufoff) + ldsw + _i * 8192), 16, 0, 0); } while (0)
; #define PG8_LDA(dst, b, h) do { _Pragma("unroll") for (int m = 0; m < 4; ++m) _Pragma("unroll") for (int k = 0; k < 2; ++k) dst[m][k] = *(const PG8_LAS bf16x8*)(lds + PG8_SA(b, h) + aoff + m * 2048 + k * 1024); } while (0)
; #define PG8_LDB(dst, b, h) do { _Pragma("unroll") for (int n = 0; n < 2; ++n) _Pragma("unroll") for (int k = 0; k < 2; ++k) dst[n][k] = *(const PG8_LAS bf16x8*)(lds + PG8_SB(b, h) + boff + n * 2048 + k * 1024); } while (0)
; #define PG8_MMA(ai, bj, At, Bt) do { __builtin_amdgcn_s_setprio(1); _Pragma("unroll") for (int m = 0; m < 4; ++m) _Pragma("unroll") for (int n = 0; n < 2; ++n) _Pragma("unroll") for (int k = 0; k < 2; ++k) \
;         acc[ai][bj][m][n] = __builtin_amdgcn_mfma_f32_16x16x32_bf16(Bt[n][k], At[m][k], acc[ai][bj][m][n], 0, 0, 0); __builtin_amdgcn_s_setprio(0); } while (0)
; #define PG8_WAIT_V(n) asm volatile("s_waitcnt vmcnt(" #n ")" ::: "memory")
; #define PG8_WAIT_L(n) asm volatile("s_waitcnt lgkmcnt(" #n ")" ::: "memory")
; #define PG8_BAR __builtin_amdgcn_s_barrier()
; #define PG8_SCHED __builtin_amdgcn_sched_barrier(0)
; template <class Epi, class Sched, bool ALIGN_EPI = false, bool SP2 = false>
; __device__ __forceinline__ void gemm_phase(PG8_LAS unsigned char* lds, const Gemm g, const Sched& S, const Epi& E) {
;     ...
;             PG8_LDB(B0, 0, 0); PG8_LDB(B1, 0, 1); PG8_SCHED; PG8_LDA(At, 0, 0); PG8_STAGE(PG8_SA(1, 1), a1 + hstep, voffA);
;             PG8_WAIT_V(8); PG8_WAIT_L(0); PG8_BAR; PG8_MMA(0, 0, At, B0); PG8_MMA(0, 1, At, B1); PG8_BAR; PG8_SCHED;
;             PG8_LDA(At, 0, 1); PG8_STAGE(PG8_SB(0, 0), b2, voffB); PG8_STAGE(PG8_SB(0, 1), b2 + hstep, voffB); PG8_STAGE(PG8_SA(0, 0), a2, voffA);
;             PG8_WAIT_V(8); PG8_WAIT_L(0); PG8_BAR; PG8_MMA(1, 0, At, B0); PG8_MMA(1, 1, At, B1); PG8_BAR; PG8_SCHED;
.Lkrot_1135:
	v_add_u32_e32 v68, s45, v169
	v_add_u32_e32 v158, s48, v169
	ds_read_b128 v[56:59], v68
	ds_read_b128 v[60:63], v68 offset:1024
	ds_read_b128 v[64:67], v68 offset:2048
	ds_read_b128 v[68:71], v68 offset:3072
	ds_read_b128 v[154:157], v158
	ds_read_b128 v[162:165], v158 offset:1024
	ds_read_b128 v[172:175], v158 offset:2048
	ds_read_b128 v[176:179], v158 offset:3072
	v_lshl_add_u64 v[158:159], s[4:5], 0, v[150:151]
	s_add_i32 m0, s27, 0xc000
	ds_read_b128 v[180:183], v171
	ds_read_b128 v[184:187], v171 offset:1024
	ds_read_b128 v[194:197], v171 offset:2048
	ds_read_b128 v[206:209], v171 offset:3072
	ds_read_b128 v[210:213], v171 offset:4096
	ds_read_b128 v[214:217], v171 offset:5120
	ds_read_b128 v[218:221], v171 offset:6144
	ds_read_b128 v[222:225], v171 offset:7168
	global_load_lds_dwordx4 v[158:159], off
	v_lshl_add_u64 v[158:159], s[4:5], 0, v[152:153]
	s_add_i32 m0, s27, 0xe000
	s_nop 0
	global_load_lds_dwordx4 v[158:159], off
	s_waitcnt vmcnt(8)
	s_waitcnt lgkmcnt(0)
	s_barrier
	s_setprio 1
	s_waitcnt lgkmcnt(0)
	v_mfma_f32_16x16x32_bf16 v[140:143], v[56:59], v[180:183], v[140:143]
	v_mfma_f32_16x16x32_bf16 v[136:139], v[64:67], v[180:183], v[136:139]
	v_mfma_f32_16x16x32_bf16 v[124:127], v[56:59], v[194:197], v[124:127]
	v_mfma_f32_16x16x32_bf16 v[120:123], v[64:67], v[194:197], v[120:123]
	v_mfma_f32_16x16x32_bf16 v[108:111], v[56:59], v[210:213], v[108:111]
	v_mfma_f32_16x16x32_bf16 v[104:107], v[64:67], v[210:213], v[104:107]
	v_mfma_f32_16x16x32_bf16 v[92:95], v[56:59], v[218:221], v[92:95]
	v_mfma_f32_16x16x32_bf16 v[88:91], v[64:67], v[218:221], v[88:91]
	v_mfma_f32_16x16x32_bf16 v[140:143], v[60:63], v[184:187], v[140:143]
	v_mfma_f32_16x16x32_bf16 v[136:139], v[68:71], v[184:187], v[136:139]
	v_mfma_f32_16x16x32_bf16 v[124:127], v[60:63], v[206:209], v[124:127]
	v_mfma_f32_16x16x32_bf16 v[120:123], v[68:71], v[206:209], v[120:123]
	v_mfma_f32_16x16x32_bf16 v[108:111], v[60:63], v[214:217], v[108:111]
	v_mfma_f32_16x16x32_bf16 v[104:107], v[68:71], v[214:217], v[104:107]
	v_mfma_f32_16x16x32_bf16 v[92:95], v[60:63], v[222:225], v[92:95]
	v_mfma_f32_16x16x32_bf16 v[88:91], v[68:71], v[222:225], v[88:91]
	s_setprio 0
	s_setprio 1
	v_mfma_f32_16x16x32_bf16 v[132:135], v[154:157], v[180:183], v[132:135]
	v_mfma_f32_16x16x32_bf16 v[128:131], v[172:175], v[180:183], v[128:131]
	v_mfma_f32_16x16x32_bf16 v[116:119], v[154:157], v[194:197], v[116:119]
	v_mfma_f32_16x16x32_bf16 v[112:115], v[172:175], v[194:197], v[112:115]
	v_mfma_f32_16x16x32_bf16 v[100:103], v[154:157], v[210:213], v[100:103]
	v_mfma_f32_16x16x32_bf16 v[96:99], v[172:175], v[210:213], v[96:99]
	v_mfma_f32_16x16x32_bf16 v[84:87], v[154:157], v[218:221], v[84:87]
	v_mfma_f32_16x16x32_bf16 v[80:83], v[172:175], v[218:221], v[80:83]
	v_mfma_f32_16x16x32_bf16 v[132:135], v[162:165], v[184:187], v[132:135]
	v_mfma_f32_16x16x32_bf16 v[128:131], v[176:179], v[184:187], v[128:131]
	v_mfma_f32_16x16x32_bf16 v[116:119], v[162:165], v[206:209], v[116:119]
	v_mfma_f32_16x16x32_bf16 v[112:115], v[176:179], v[206:209], v[112:115]
	v_mfma_f32_16x16x32_bf16 v[100:103], v[162:165], v[214:217], v[100:103]
	v_mfma_f32_16x16x32_bf16 v[96:99], v[176:179], v[214:217], v[96:99]
	v_mfma_f32_16x16x32_bf16 v[84:87], v[162:165], v[222:225], v[84:87]
	v_mfma_f32_16x16x32_bf16 v[80:83], v[176:179], v[222:225], v[80:83]
	s_setprio 0
	s_barrier
	s_add_i32 s45, s45, s26
	v_lshl_add_u64 v[158:159], s[18:19], 0, v[160:161]
	s_mov_b32 m0, s45
	ds_read_b128 v[180:183], v171 offset:16384
	ds_read_b128 v[184:187], v171 offset:17408
	ds_read_b128 v[194:197], v171 offset:18432
	ds_read_b128 v[206:209], v171 offset:19456
	ds_read_b128 v[210:213], v171 offset:20480
	ds_read_b128 v[214:217], v171 offset:21504
	ds_read_b128 v[218:221], v171 offset:22528
	ds_read_b128 v[222:225], v171 offset:23552
	global_load_lds_dwordx4 v[158:159], off
	s_add_i32 m0, s45, 0x2000
	s_add_u32 s46, s18, 0x40000
	v_lshl_add_u64 v[166:167], s[18:19], 0, v[144:145]
	s_addc_u32 s47, s19, 0
	s_add_i32 s45, s48, s26
	global_load_lds_dwordx4 v[166:167], off
	v_lshl_add_u64 v[188:189], s[46:47], 0, v[160:161]
	s_mov_b32 m0, s45
	v_lshl_add_u64 v[226:227], s[20:21], 0, v[146:147]
	global_load_lds_dwordx4 v[188:189], off
	v_lshl_add_u64 v[188:189], s[46:47], 0, v[144:145]
	s_add_i32 m0, s45, 0x2000
	s_nop 0
	global_load_lds_dwordx4 v[188:189], off
	v_lshl_add_u64 v[188:189], s[20:21], 0, v[148:149]
	s_mov_b32 m0, s27
	s_nop 0
	global_load_lds_dwordx4 v[188:189], off
	s_mov_b32 m0, s28
	s_nop 0
	global_load_lds_dwordx4 v[226:227], off
	s_waitcnt vmcnt(8)
	s_waitcnt lgkmcnt(0)
	s_barrier
; #define PG8_STAGE(bufoff, gbase, voff) do { _Pragma("unroll") for (int _i = 0; _i < 2; ++_i) \
;         __builtin_amdgcn_global_load_lds((const unsigned*)((const char*)(gbase) + (voff)[_i]), (PG8_LAS unsigned*)(lds + (bufoff) + ldsw + _i * 8192), 16, 0, 0); } while (0)
; #define PG8_LDA(dst, b, h) do { _Pragma("unroll") for (int m = 0; m < 4; ++m) _Pragma("unroll") for (int k = 0; k < 2; ++k) dst[m][k] = *(const PG8_LAS bf16x8*)(lds + PG8_SA(b, h) + aoff + m * 2048 + k * 1024); } while (0)
; #define PG8_LDB(dst, b, h) do { _Pragma("unroll") for (int n = 0; n < 2; ++n) _Pragma("unroll") for (int k = 0; k < 2; ++k) dst[n][k] = *(const PG8_LAS bf16x8*)(lds + PG8_SB(b, h) + boff + n * 2048 + k * 1024); } while (0)
; #define PG8_MMA(ai, bj, At, Bt) do { __builtin_amdgcn_s_setprio(1); _Pragma("unroll") for (int m = 0; m < 4; ++m) _Pragma("unroll") for (int n = 0; n < 2; ++n) _Pragma("unroll") for (int k = 0; k < 2; ++k) \
;         acc[ai][bj][m][n] = __builtin_amdgcn_mfma_f32_16x16x32_bf16(Bt[n][k], At[m][k], acc[ai][bj][m][n], 0, 0, 0); __builtin_amdgcn_s_setprio(0); } while (0)
; #define PG8_WAIT_V(n) asm volatile("s_waitcnt vmcnt(" #n ")" ::: "memory")
; #define PG8_WAIT_L(n) asm volatile("s_waitcnt lgkmcnt(" #n ")" ::: "memory")
; #define PG8_BAR __builtin_amdgcn_s_barrier()
; #define PG8_SCHED __builtin_amdgcn_sched_barrier(0)
; template <class Epi, class Sched, bool ALIGN_EPI = false, bool SP2 = false>
; __device__ __forceinline__ void gemm_phase(PG8_LAS unsigned char* lds, const Gemm g, const Sched& S, const Epi& E) {
;     ...
;             PG8_WAIT_V(8); PG8_WAIT_L(0); PG8_BAR; PG8_MMA(1, 0, At, B0); PG8_MMA(1, 1, At, B1); PG8_BAR; PG8_SCHED;
;             PG8_LDB(B0, 1, 0); PG8_LDB(B1, 1, 1); PG8_SCHED; PG8_LDA(At, 1, 0); PG8_STAGE(PG8_SA(0, 1), a2 + hstep, voffA);
;             PG8_WAIT_V(8); PG8_WAIT_L(0); PG8_BAR; PG8_MMA(0, 0, At, B0); PG8_MMA(0, 1, At, B1); PG8_BAR; PG8_SCHED;
	s_setprio 1
	s_waitcnt lgkmcnt(0)
	v_mfma_f32_16x16x32_bf16 v[76:79], v[56:59], v[180:183], v[76:79]
	v_mfma_f32_16x16x32_bf16 v[72:75], v[64:67], v[180:183], v[72:75]
	v_mfma_f32_16x16x32_bf16 v[44:47], v[56:59], v[194:197], v[44:47]
	v_mfma_f32_16x16x32_bf16 v[40:43], v[64:67], v[194:197], v[40:43]
	v_mfma_f32_16x16x32_bf16 v[28:31], v[56:59], v[210:213], v[28:31]
	v_mfma_f32_16x16x32_bf16 v[24:27], v[64:67], v[210:213], v[24:27]
	v_mfma_f32_16x16x32_bf16 v[12:15], v[56:59], v[218:221], v[12:15]
	v_mfma_f32_16x16x32_bf16 v[8:11], v[64:67], v[218:221], v[8:11]
	v_mfma_f32_16x16x32_bf16 v[76:79], v[60:63], v[184:187], v[76:79]
	v_mfma_f32_16x16x32_bf16 v[72:75], v[68:71], v[184:187], v[72:75]
	v_mfma_f32_16x16x32_bf16 v[44:47], v[60:63], v[206:209], v[44:47]
	v_mfma_f32_16x16x32_bf16 v[40:43], v[68:71], v[206:209], v[40:43]
	v_mfma_f32_16x16x32_bf16 v[28:31], v[60:63], v[214:217], v[28:31]
	v_mfma_f32_16x16x32_bf16 v[24:27], v[68:71], v[214:217], v[24:27]
	v_mfma_f32_16x16x32_bf16 v[12:15], v[60:63], v[222:225], v[12:15]
	v_mfma_f32_16x16x32_bf16 v[8:11], v[68:71], v[222:225], v[8:11]
	s_setprio 0
	s_setprio 1
	v_mfma_f32_16x16x32_bf16 v[52:55], v[154:157], v[180:183], v[52:55]
	v_mfma_f32_16x16x32_bf16 v[48:51], v[172:175], v[180:183], v[48:51]
	v_mfma_f32_16x16x32_bf16 v[36:39], v[154:157], v[194:197], v[36:39]
	v_mfma_f32_16x16x32_bf16 v[32:35], v[172:175], v[194:197], v[32:35]
	v_mfma_f32_16x16x32_bf16 v[20:23], v[154:157], v[210:213], v[20:23]
	v_mfma_f32_16x16x32_bf16 v[16:19], v[172:175], v[210:213], v[16:19]
	v_mfma_f32_16x16x32_bf16 v[4:7], v[154:157], v[218:221], v[4:7]
	v_mfma_f32_16x16x32_bf16 v[0:3], v[172:175], v[218:221], v[0:3]
	v_mfma_f32_16x16x32_bf16 v[52:55], v[162:165], v[184:187], v[52:55]
	v_mfma_f32_16x16x32_bf16 v[48:51], v[176:179], v[184:187], v[48:51]
	v_mfma_f32_16x16x32_bf16 v[36:39], v[162:165], v[206:209], v[36:39]
	v_mfma_f32_16x16x32_bf16 v[32:35], v[176:179], v[206:209], v[32:35]
	v_mfma_f32_16x16x32_bf16 v[20:23], v[162:165], v[214:217], v[20:23]
	v_mfma_f32_16x16x32_bf16 v[16:19], v[176:179], v[214:217], v[16:19]
	v_mfma_f32_16x16x32_bf16 v[4:7], v[162:165], v[222:225], v[4:7]
	v_mfma_f32_16x16x32_bf16 v[0:3], v[176:179], v[222:225], v[0:3]
	s_setprio 0
	s_barrier
	s_add_i32 s45, 0, 0x18000
	s_add_i32 s46, 0, 0x1c000
	v_add_u32_e32 v68, s45, v169
	v_add_u32_e32 v176, s46, v169
	ds_read_b128 v[56:59], v68
	ds_read_b128 v[60:63], v68 offset:1024
	ds_read_b128 v[64:67], v68 offset:2048
	ds_read_b128 v[68:71], v68 offset:3072
	ds_read_b128 v[154:157], v176
	ds_read_b128 v[162:165], v176 offset:1024
	ds_read_b128 v[172:175], v176 offset:2048
	ds_read_b128 v[176:179], v176 offset:3072
	s_add_u32 s20, s20, 0x40000
	s_addc_u32 s21, s21, 0
	s_mov_b32 m0, s29
	v_lshl_add_u64 v[228:229], s[20:21], 0, v[148:149]
	ds_read_b128 v[180:183], v171 offset:32768
	ds_read_b128 v[184:187], v171 offset:33792
	ds_read_b128 v[194:197], v171 offset:34816
	ds_read_b128 v[206:209], v171 offset:35840
	ds_read_b128 v[210:213], v171 offset:36864
	ds_read_b128 v[214:217], v171 offset:37888
	ds_read_b128 v[218:221], v171 offset:38912
	ds_read_b128 v[222:225], v171 offset:39936
	global_load_lds_dwordx4 v[228:229], off
	v_lshl_add_u64 v[228:229], s[20:21], 0, v[146:147]
	s_mov_b32 m0, s30
	s_nop 0
	global_load_lds_dwordx4 v[228:229], off
	s_waitcnt vmcnt(8)
	s_waitcnt lgkmcnt(0)
	s_barrier
	s_setprio 1
	s_waitcnt lgkmcnt(0)
	v_mfma_f32_16x16x32_bf16 v[140:143], v[56:59], v[180:183], v[140:143]
	v_mfma_f32_16x16x32_bf16 v[136:139], v[64:67], v[180:183], v[136:139]
	v_mfma_f32_16x16x32_bf16 v[124:127], v[56:59], v[194:197], v[124:127]
	v_mfma_f32_16x16x32_bf16 v[120:123], v[64:67], v[194:197], v[120:123]
	v_mfma_f32_16x16x32_bf16 v[108:111], v[56:59], v[210:213], v[108:111]
	v_mfma_f32_16x16x32_bf16 v[104:107], v[64:67], v[210:213], v[104:107]
	v_mfma_f32_16x16x32_bf16 v[92:95], v[56:59], v[218:221], v[92:95]
	v_mfma_f32_16x16x32_bf16 v[88:91], v[64:67], v[218:221], v[88:91]
	v_mfma_f32_16x16x32_bf16 v[140:143], v[60:63], v[184:187], v[140:143]
	v_mfma_f32_16x16x32_bf16 v[136:139], v[68:71], v[184:187], v[136:139]
	v_mfma_f32_16x16x32_bf16 v[124:127], v[60:63], v[206:209], v[124:127]
	v_mfma_f32_16x16x32_bf16 v[120:123], v[68:71], v[206:209], v[120:123]
	v_mfma_f32_16x16x32_bf16 v[108:111], v[60:63], v[214:217], v[108:111]
	v_mfma_f32_16x16x32_bf16 v[104:107], v[68:71], v[214:217], v[104:107]
	v_mfma_f32_16x16x32_bf16 v[92:95], v[60:63], v[222:225], v[92:95]
	v_mfma_f32_16x16x32_bf16 v[88:91], v[68:71], v[222:225], v[88:91]
	s_setprio 0
	s_setprio 1
	v_mfma_f32_16x16x32_bf16 v[132:135], v[154:157], v[180:183], v[132:135]
	v_mfma_f32_16x16x32_bf16 v[128:131], v[172:175], v[180:183], v[128:131]
	v_mfma_f32_16x16x32_bf16 v[116:119], v[154:157], v[194:197], v[116:119]
	v_mfma_f32_16x16x32_bf16 v[112:115], v[172:175], v[194:197], v[112:115]
	v_mfma_f32_16x16x32_bf16 v[100:103], v[154:157], v[210:213], v[100:103]
	v_mfma_f32_16x16x32_bf16 v[96:99], v[172:175], v[210:213], v[96:99]
	v_mfma_f32_16x16x32_bf16 v[84:87], v[154:157], v[218:221], v[84:87]
	v_mfma_f32_16x16x32_bf16 v[80:83], v[172:175], v[218:221], v[80:83]
	v_mfma_f32_16x16x32_bf16 v[132:135], v[162:165], v[184:187], v[132:135]
	v_mfma_f32_16x16x32_bf16 v[128:131], v[176:179], v[184:187], v[128:131]
	v_mfma_f32_16x16x32_bf16 v[116:119], v[162:165], v[206:209], v[116:119]
	v_mfma_f32_16x16x32_bf16 v[112:115], v[176:179], v[206:209], v[112:115]
	v_mfma_f32_16x16x32_bf16 v[100:103], v[162:165], v[214:217], v[100:103]
	v_mfma_f32_16x16x32_bf16 v[96:99], v[176:179], v[214:217], v[96:99]
	v_mfma_f32_16x16x32_bf16 v[84:87], v[162:165], v[222:225], v[84:87]
	v_mfma_f32_16x16x32_bf16 v[80:83], v[176:179], v[222:225], v[80:83]
	s_setprio 0
	s_barrier
; #define PG8_STAGE(bufoff, gbase, voff) do { _Pragma("unroll") for (int _i = 0; _i < 2; ++_i) \
;         __builtin_amdgcn_global_load_lds((const unsigned*)((const char*)(gbase) + (voff)[_i]), (PG8_LAS unsigned*)(lds + (bufoff) + ldsw + _i * 8192), 16, 0, 0); } while (0)
; #define PG8_LDA(dst, b, h) do { _Pragma("unroll") for (int m = 0; m < 4; ++m) _Pragma("unroll") for (int k = 0; k < 2; ++k) dst[m][k] = *(const PG8_LAS bf16x8*)(lds + PG8_SA(b, h) + aoff + m * 2048 + k * 1024); } while (0)
; #define PG8_MMA(ai, bj, At, Bt) do { __builtin_amdgcn_s_setprio(1); _Pragma("unroll") for (int m = 0; m < 4; ++m) _Pragma("unroll") for (int n = 0; n < 2; ++n) _Pragma("unroll") for (int k = 0; k < 2; ++k) \
;         acc[ai][bj][m][n] = __builtin_amdgcn_mfma_f32_16x16x32_bf16(Bt[n][k], At[m][k], acc[ai][bj][m][n], 0, 0, 0); __builtin_amdgcn_s_setprio(0); } while (0)
; #define PG8_WAIT_V(n) asm volatile("s_waitcnt vmcnt(" #n ")" ::: "memory")
; #define PG8_WAIT_L(n) asm volatile("s_waitcnt lgkmcnt(" #n ")" ::: "memory")
; #define PG8_BAR __builtin_amdgcn_s_barrier()
; #define PG8_SCHED __builtin_amdgcn_sched_barrier(0)
; template <class Epi, class Sched, bool ALIGN_EPI = false, bool SP2 = false>
; __device__ __forceinline__ void gemm_phase(PG8_LAS unsigned char* lds, const Gemm g, const Sched& S, const Epi& E) {
;     ...
;         for (int t = 0; t < nt; t += 2) {
;             const bool last = (t == nt - 2);
;             const char* a1 = cA + (size_t)(t + 1) * kstep;
;             const char* a2 = last ? nA : cA + (size_t)(t + 2) * kstep; const char* b2 = last ? nB : cB + (size_t)(t + 2) * kstep;
;             const char* a3 = a2 + kstep; const char* b3 = b2 + kstep;
;             if (last && has_next) S.a_ready(nxt);
;     ...
;             PG8_LDA(At, 1, 1); PG8_STAGE(PG8_SB(1, 0), b3, voffB); PG8_STAGE(PG8_SB(1, 1), b3 + hstep, voffB); PG8_STAGE(PG8_SA(1, 0), a3, voffA);
;             PG8_WAIT_V(8); PG8_WAIT_L(0); PG8_BAR; PG8_MMA(1, 0, At, B0); PG8_MMA(1, 1, At, B1); PG8_BAR; PG8_SCHED;
	s_add_i32 s20, s45, s26
	v_lshl_add_u64 v[158:159], v[158:159], 0, s[38:39]
	s_mov_b32 m0, s20
	ds_read_b128 v[180:183], v171 offset:49152
	ds_read_b128 v[184:187], v171 offset:50176
	ds_read_b128 v[194:197], v171 offset:51200
	ds_read_b128 v[206:209], v171 offset:52224
	ds_read_b128 v[210:213], v171 offset:53248
	ds_read_b128 v[214:217], v171 offset:54272
	ds_read_b128 v[218:221], v171 offset:55296
	ds_read_b128 v[222:225], v171 offset:56320
	global_load_lds_dwordx4 v[158:159], off
	s_add_i32 m0, s20, 0x2000
	s_add_u32 s18, s18, 0x40080
	v_lshl_add_u64 v[158:159], v[166:167], 0, s[38:39]
	s_addc_u32 s19, s19, 0
	s_add_i32 s20, s46, s26
	global_load_lds_dwordx4 v[158:159], off
	v_lshl_add_u64 v[158:159], s[18:19], 0, v[160:161]
	s_mov_b32 m0, s20
	s_nop 0
	global_load_lds_dwordx4 v[158:159], off
	v_lshl_add_u64 v[158:159], s[18:19], 0, v[144:145]
	s_add_i32 m0, s20, 0x2000
	s_nop 0
	global_load_lds_dwordx4 v[158:159], off
	v_lshl_add_u64 v[158:159], v[188:189], 0, s[38:39]
	s_mov_b32 m0, s35
	s_nop 0
	global_load_lds_dwordx4 v[158:159], off
	v_lshl_add_u64 v[158:159], v[226:227], 0, s[38:39]
	s_mov_b32 m0, s36
	s_nop 0
	global_load_lds_dwordx4 v[158:159], off
	s_waitcnt vmcnt(8)
	s_waitcnt lgkmcnt(0)
	s_barrier
	s_setprio 1
	s_waitcnt lgkmcnt(0)
	v_mfma_f32_16x16x32_bf16 v[76:79], v[56:59], v[180:183], v[76:79]
	v_mfma_f32_16x16x32_bf16 v[72:75], v[64:67], v[180:183], v[72:75]
	v_mfma_f32_16x16x32_bf16 v[44:47], v[56:59], v[194:197], v[44:47]
	v_mfma_f32_16x16x32_bf16 v[40:43], v[64:67], v[194:197], v[40:43]
	v_mfma_f32_16x16x32_bf16 v[28:31], v[56:59], v[210:213], v[28:31]
	v_mfma_f32_16x16x32_bf16 v[24:27], v[64:67], v[210:213], v[24:27]
	v_mfma_f32_16x16x32_bf16 v[12:15], v[56:59], v[218:221], v[12:15]
	v_mfma_f32_16x16x32_bf16 v[8:11], v[64:67], v[218:221], v[8:11]
	v_mfma_f32_16x16x32_bf16 v[76:79], v[60:63], v[184:187], v[76:79]
	v_mfma_f32_16x16x32_bf16 v[72:75], v[68:71], v[184:187], v[72:75]
	v_mfma_f32_16x16x32_bf16 v[44:47], v[60:63], v[206:209], v[44:47]
	v_mfma_f32_16x16x32_bf16 v[40:43], v[68:71], v[206:209], v[40:43]
	v_mfma_f32_16x16x32_bf16 v[28:31], v[60:63], v[214:217], v[28:31]
	v_mfma_f32_16x16x32_bf16 v[24:27], v[68:71], v[214:217], v[24:27]
	v_mfma_f32_16x16x32_bf16 v[12:15], v[60:63], v[222:225], v[12:15]
	v_mfma_f32_16x16x32_bf16 v[8:11], v[68:71], v[222:225], v[8:11]
	s_setprio 0
	s_setprio 1
	v_mfma_f32_16x16x32_bf16 v[52:55], v[154:157], v[180:183], v[52:55]
	v_mfma_f32_16x16x32_bf16 v[48:51], v[172:175], v[180:183], v[48:51]
	v_mfma_f32_16x16x32_bf16 v[36:39], v[154:157], v[194:197], v[36:39]
	v_mfma_f32_16x16x32_bf16 v[32:35], v[172:175], v[194:197], v[32:35]
	v_mfma_f32_16x16x32_bf16 v[20:23], v[154:157], v[210:213], v[20:23]
	v_mfma_f32_16x16x32_bf16 v[16:19], v[172:175], v[210:213], v[16:19]
	v_mfma_f32_16x16x32_bf16 v[4:7], v[154:157], v[218:221], v[4:7]
	v_mfma_f32_16x16x32_bf16 v[0:3], v[172:175], v[218:221], v[0:3]
	v_mfma_f32_16x16x32_bf16 v[52:55], v[162:165], v[184:187], v[52:55]
	v_mfma_f32_16x16x32_bf16 v[48:51], v[176:179], v[184:187], v[48:51]
	v_mfma_f32_16x16x32_bf16 v[36:39], v[162:165], v[206:209], v[36:39]
	v_mfma_f32_16x16x32_bf16 v[32:35], v[176:179], v[206:209], v[32:35]
	v_mfma_f32_16x16x32_bf16 v[20:23], v[162:165], v[214:217], v[20:23]
	v_mfma_f32_16x16x32_bf16 v[16:19], v[176:179], v[214:217], v[16:19]
	v_mfma_f32_16x16x32_bf16 v[4:7], v[162:165], v[222:225], v[4:7]
	v_mfma_f32_16x16x32_bf16 v[0:3], v[176:179], v[222:225], v[0:3]
	s_setprio 0
	s_add_i32 s44, s44, 2
	s_add_u32 s4, s4, 0x100
	s_addc_u32 s5, s5, 0
	s_add_u32 s42, s42, 0x100
	s_addc_u32 s43, s43, 0
	s_add_u32 s18, s4, 0xfffc0080
	s_addc_u32 s19, s5, -1
	s_add_i32 s45, 0, 0x10000
	s_cmp_eq_u32 s44, 12
	s_cselect_b32 s21, s11, s19
	s_cselect_b32 s20, s40, s18
	s_cselect_b32 s19, s13, s43
	s_cselect_b32 s18, s41, s42
	s_add_i32 s48, 0, 0x14000
	s_cmp_gt_u32 s44, 13
	s_barrier
	s_cbranch_scc0 .Lkrot_1135
	s_and_b64 vcc, exec, s[6:7]
	s_cbranch_vccz .LBB0_1138
	s_barrier

; #define PG8_STAGE(bufoff, gbase, voff) do { _Pragma("unroll") for (int _i = 0; _i < 2; ++_i) \
;         __builtin_amdgcn_global_load_lds((const unsigned*)((const char*)(gbase) + (voff)[_i]), (PG8_LAS unsigned*)(lds + (bufoff) + ldsw + _i * 8192), 16, 0, 0); } while (0)
; #define PG8_LDA(dst, b, h) do { _Pragma("unroll") for (int m = 0; m < 4; ++m) _Pragma("unroll") for (int k = 0; k < 2; ++k) dst[m][k] = *(const PG8_LAS bf16x8*)(lds + PG8_SA(b, h) + aoff + m * 2048 + k * 1024); } while (0)
; #define PG8_LDB(dst, b, h) do { _Pragma("unroll") for (int n = 0; n < 2; ++n) _Pragma("unroll") for (int k = 0; k < 2; ++k) dst[n][k] = *(const PG8_LAS bf16x8*)(lds + PG8_SB(b, h) + boff + n * 2048 + k * 1024); } while (0)
; #define PG8_MMA(ai, bj, At, Bt) do { __builtin_amdgcn_s_setprio(1); _Pragma("unroll") for (int m = 0; m < 4; ++m) _Pragma("unroll") for (int n = 0; n < 2; ++n) _Pragma("unroll") for (int k = 0; k < 2; ++k) \
;         acc[ai][bj][m][n] = __builtin_amdgcn_mfma_f32_16x16x32_bf16(Bt[n][k], At[m][k], acc[ai][bj][m][n], 0, 0, 0); __builtin_amdgcn_s_setprio(0); } while (0)
; #define PG8_WAIT_V(n) asm volatile("s_waitcnt vmcnt(" #n ")" ::: "memory")
; #define PG8_WAIT_L(n) asm volatile("s_waitcnt lgkmcnt(" #n ")" ::: "memory")
; #define PG8_BAR __builtin_amdgcn_s_barrier()
; #define PG8_SCHED __builtin_amdgcn_sched_barrier(0)
; template <class Epi, class Sched, bool ALIGN_EPI = false, bool SP2 = false>
; __device__ __forceinline__ void gemm_phase(PG8_LAS unsigned char* lds, const Gemm g, const Sched& S, const Epi& E) {
;     ...
;             PG8_LDB(B0, 0, 0); PG8_LDB(B1, 0, 1); PG8_SCHED; PG8_LDA(At, 0, 0); PG8_STAGE(PG8_SA(1, 1), a1 + hstep, voffA);
;             PG8_WAIT_V(8); PG8_WAIT_L(0); PG8_BAR; PG8_MMA(0, 0, At, B0); PG8_MMA(0, 1, At, B1); PG8_BAR; PG8_SCHED;
;             PG8_LDA(At, 0, 1); PG8_STAGE(PG8_SB(0, 0), b2, voffB); PG8_STAGE(PG8_SB(0, 1), b2 + hstep, voffB); PG8_STAGE(PG8_SA(0, 0), a2, voffA);
;             PG8_WAIT_V(8); PG8_WAIT_L(0); PG8_BAR; PG8_MMA(1, 0, At, B0); PG8_MMA(1, 1, At, B1); PG8_BAR; PG8_SCHED;
.Lkrot_1215:
	v_add_u32_e32 v76, s47, v188
	v_add_u32_e32 v158, s50, v188
	ds_read_b128 v[56:59], v76
	ds_read_b128 v[60:63], v76 offset:1024
	ds_read_b128 v[68:71], v76 offset:2048
	ds_read_b128 v[76:79], v76 offset:3072
	ds_read_b128 v[144:147], v158
	ds_read_b128 v[162:165], v158 offset:1024
	ds_read_b128 v[166:169], v158 offset:2048
	ds_read_b128 v[170:173], v158 offset:3072
	v_lshl_add_u64 v[158:159], s[2:3], 0, v[154:155]
	s_add_i32 m0, s29, 0xc000
	ds_read_b128 v[174:177], v189
	ds_read_b128 v[178:181], v189 offset:1024
	ds_read_b128 v[182:185], v189 offset:2048
	ds_read_b128 v[194:197], v189 offset:3072
	ds_read_b128 v[206:209], v189 offset:4096
	ds_read_b128 v[210:213], v189 offset:5120
	ds_read_b128 v[214:217], v189 offset:6144
	ds_read_b128 v[218:221], v189 offset:7168
	global_load_lds_dwordx4 v[158:159], off
	v_lshl_add_u64 v[158:159], s[2:3], 0, v[156:157]
	s_add_i32 m0, s29, 0xe000
	s_nop 0
	global_load_lds_dwordx4 v[158:159], off
	s_waitcnt vmcnt(8)
	s_waitcnt lgkmcnt(0)
	s_barrier
	s_setprio 1
	s_waitcnt lgkmcnt(0)
	v_mfma_f32_16x16x32_bf16 v[64:67], v[56:59], v[174:177], v[64:67]
	v_mfma_f32_16x16x32_bf16 v[140:143], v[68:71], v[174:177], v[140:143]
	v_mfma_f32_16x16x32_bf16 v[128:131], v[56:59], v[182:185], v[128:131]
	v_mfma_f32_16x16x32_bf16 v[124:127], v[68:71], v[182:185], v[124:127]
	v_mfma_f32_16x16x32_bf16 v[112:115], v[56:59], v[206:209], v[112:115]
	v_mfma_f32_16x16x32_bf16 v[108:111], v[68:71], v[206:209], v[108:111]
	v_mfma_f32_16x16x32_bf16 v[96:99], v[56:59], v[214:217], v[96:99]
	v_mfma_f32_16x16x32_bf16 v[92:95], v[68:71], v[214:217], v[92:95]
	v_mfma_f32_16x16x32_bf16 v[64:67], v[60:63], v[178:181], v[64:67]
	v_mfma_f32_16x16x32_bf16 v[140:143], v[76:79], v[178:181], v[140:143]
	v_mfma_f32_16x16x32_bf16 v[128:131], v[60:63], v[194:197], v[128:131]
	v_mfma_f32_16x16x32_bf16 v[124:127], v[76:79], v[194:197], v[124:127]
	v_mfma_f32_16x16x32_bf16 v[112:115], v[60:63], v[210:213], v[112:115]
	v_mfma_f32_16x16x32_bf16 v[108:111], v[76:79], v[210:213], v[108:111]
	v_mfma_f32_16x16x32_bf16 v[96:99], v[60:63], v[218:221], v[96:99]
	v_mfma_f32_16x16x32_bf16 v[92:95], v[76:79], v[218:221], v[92:95]
	s_setprio 0
	s_setprio 1
	v_mfma_f32_16x16x32_bf16 v[136:139], v[144:147], v[174:177], v[136:139]
	v_mfma_f32_16x16x32_bf16 v[132:135], v[166:169], v[174:177], v[132:135]
	v_mfma_f32_16x16x32_bf16 v[120:123], v[144:147], v[182:185], v[120:123]
	v_mfma_f32_16x16x32_bf16 v[116:119], v[166:169], v[182:185], v[116:119]
	v_mfma_f32_16x16x32_bf16 v[104:107], v[144:147], v[206:209], v[104:107]
	v_mfma_f32_16x16x32_bf16 v[100:103], v[166:169], v[206:209], v[100:103]
	v_mfma_f32_16x16x32_bf16 v[88:91], v[144:147], v[214:217], v[88:91]
	v_mfma_f32_16x16x32_bf16 v[84:87], v[166:169], v[214:217], v[84:87]
	v_mfma_f32_16x16x32_bf16 v[136:139], v[162:165], v[178:181], v[136:139]
	v_mfma_f32_16x16x32_bf16 v[132:135], v[170:173], v[178:181], v[132:135]
	v_mfma_f32_16x16x32_bf16 v[120:123], v[162:165], v[194:197], v[120:123]
	v_mfma_f32_16x16x32_bf16 v[116:119], v[170:173], v[194:197], v[116:119]
	v_mfma_f32_16x16x32_bf16 v[104:107], v[162:165], v[210:213], v[104:107]
	v_mfma_f32_16x16x32_bf16 v[100:103], v[170:173], v[210:213], v[100:103]
	v_mfma_f32_16x16x32_bf16 v[88:91], v[162:165], v[218:221], v[88:91]
	v_mfma_f32_16x16x32_bf16 v[84:87], v[170:173], v[218:221], v[84:87]
	s_setprio 0
	s_barrier
	s_add_i32 s47, s47, s28
	v_lshl_add_u64 v[158:159], s[4:5], 0, v[160:161]
	s_mov_b32 m0, s47
	ds_read_b128 v[174:177], v189 offset:16384
	ds_read_b128 v[178:181], v189 offset:17408
	ds_read_b128 v[182:185], v189 offset:18432
	ds_read_b128 v[194:197], v189 offset:19456
	ds_read_b128 v[206:209], v189 offset:20480
	ds_read_b128 v[210:213], v189 offset:21504
	ds_read_b128 v[214:217], v189 offset:22528
	ds_read_b128 v[218:221], v189 offset:23552
	global_load_lds_dwordx4 v[158:159], off
	s_add_i32 m0, s47, 0x2000
	s_add_u32 s48, s4, 0x100000
	v_lshl_add_u64 v[186:187], s[4:5], 0, v[148:149]
	s_addc_u32 s49, s5, 0
	s_add_i32 s47, s50, s28
	global_load_lds_dwordx4 v[186:187], off
	v_lshl_add_u64 v[222:223], s[48:49], 0, v[160:161]
	s_mov_b32 m0, s47
	v_lshl_add_u64 v[224:225], s[22:23], 0, v[150:151]
	global_load_lds_dwordx4 v[222:223], off
	v_lshl_add_u64 v[222:223], s[48:49], 0, v[148:149]
	s_add_i32 m0, s47, 0x2000
	s_nop 0
	global_load_lds_dwordx4 v[222:223], off
	v_lshl_add_u64 v[222:223], s[22:23], 0, v[152:153]
	s_mov_b32 m0, s29
	s_nop 0
	global_load_lds_dwordx4 v[222:223], off
	s_mov_b32 m0, s30
	s_nop 0
	global_load_lds_dwordx4 v[224:225], off
	s_waitcnt vmcnt(8)
	s_waitcnt lgkmcnt(0)
	s_barrier
; #define PG8_STAGE(bufoff, gbase, voff) do { _Pragma("unroll") for (int _i = 0; _i < 2; ++_i) \
;         __builtin_amdgcn_global_load_lds((const unsigned*)((const char*)(gbase) + (voff)[_i]), (PG8_LAS unsigned*)(lds + (bufoff) + ldsw + _i * 8192), 16, 0, 0); } while (0)
; #define PG8_LDA(dst, b, h) do { _Pragma("unroll") for (int m = 0; m < 4; ++m) _Pragma("unroll") for (int k = 0; k < 2; ++k) dst[m][k] = *(const PG8_LAS bf16x8*)(lds + PG8_SA(b, h) + aoff + m * 2048 + k * 1024); } while (0)
; #define PG8_LDB(dst, b, h) do { _Pragma("unroll") for (int n = 0; n < 2; ++n) _Pragma("unroll") for (int k = 0; k < 2; ++k) dst[n][k] = *(const PG8_LAS bf16x8*)(lds + PG8_SB(b, h) + boff + n * 2048 + k * 1024); } while (0)
; #define PG8_MMA(ai, bj, At, Bt) do { __builtin_amdgcn_s_setprio(1); _Pragma("unroll") for (int m = 0; m < 4; ++m) _Pragma("unroll") for (int n = 0; n < 2; ++n) _Pragma("unroll") for (int k = 0; k < 2; ++k) \
;         acc[ai][bj][m][n] = __builtin_amdgcn_mfma_f32_16x16x32_bf16(Bt[n][k], At[m][k], acc[ai][bj][m][n], 0, 0, 0); __builtin_amdgcn_s_setprio(0); } while (0)
; #define PG8_WAIT_V(n) asm volatile("s_waitcnt vmcnt(" #n ")" ::: "memory")
; #define PG8_WAIT_L(n) asm volatile("s_waitcnt lgkmcnt(" #n ")" ::: "memory")
; #define PG8_BAR __builtin_amdgcn_s_barrier()
; #define PG8_SCHED __builtin_amdgcn_sched_barrier(0)
; template <class Epi, class Sched, bool ALIGN_EPI = false, bool SP2 = false>
; __device__ __forceinline__ void gemm_phase(PG8_LAS unsigned char* lds, const Gemm g, const Sched& S, const Epi& E) {
;     ...
;             PG8_WAIT_V(8); PG8_WAIT_L(0); PG8_BAR; PG8_MMA(1, 0, At, B0); PG8_MMA(1, 1, At, B1); PG8_BAR; PG8_SCHED;
;             PG8_LDB(B0, 1, 0); PG8_LDB(B1, 1, 1); PG8_SCHED; PG8_LDA(At, 1, 0); PG8_STAGE(PG8_SA(0, 1), a2 + hstep, voffA);
;             PG8_WAIT_V(8); PG8_WAIT_L(0); PG8_BAR; PG8_MMA(0, 0, At, B0); PG8_MMA(0, 1, At, B1); PG8_BAR; PG8_SCHED;
	s_setprio 1
	s_waitcnt lgkmcnt(0)
	v_mfma_f32_16x16x32_bf16 v[80:83], v[56:59], v[174:177], v[80:83]
	v_mfma_f32_16x16x32_bf16 v[72:75], v[68:71], v[174:177], v[72:75]
	v_mfma_f32_16x16x32_bf16 v[44:47], v[56:59], v[182:185], v[44:47]
	v_mfma_f32_16x16x32_bf16 v[40:43], v[68:71], v[182:185], v[40:43]
	v_mfma_f32_16x16x32_bf16 v[28:31], v[56:59], v[206:209], v[28:31]
	v_mfma_f32_16x16x32_bf16 v[24:27], v[68:71], v[206:209], v[24:27]
	v_mfma_f32_16x16x32_bf16 v[12:15], v[56:59], v[214:217], v[12:15]
	v_mfma_f32_16x16x32_bf16 v[8:11], v[68:71], v[214:217], v[8:11]
	v_mfma_f32_16x16x32_bf16 v[80:83], v[60:63], v[178:181], v[80:83]
	v_mfma_f32_16x16x32_bf16 v[72:75], v[76:79], v[178:181], v[72:75]
	v_mfma_f32_16x16x32_bf16 v[44:47], v[60:63], v[194:197], v[44:47]
	v_mfma_f32_16x16x32_bf16 v[40:43], v[76:79], v[194:197], v[40:43]
	v_mfma_f32_16x16x32_bf16 v[28:31], v[60:63], v[210:213], v[28:31]
	v_mfma_f32_16x16x32_bf16 v[24:27], v[76:79], v[210:213], v[24:27]
	v_mfma_f32_16x16x32_bf16 v[12:15], v[60:63], v[218:221], v[12:15]
	v_mfma_f32_16x16x32_bf16 v[8:11], v[76:79], v[218:221], v[8:11]
	s_setprio 0
	s_setprio 1
	v_mfma_f32_16x16x32_bf16 v[52:55], v[144:147], v[174:177], v[52:55]
	v_mfma_f32_16x16x32_bf16 v[48:51], v[166:169], v[174:177], v[48:51]
	v_mfma_f32_16x16x32_bf16 v[36:39], v[144:147], v[182:185], v[36:39]
	v_mfma_f32_16x16x32_bf16 v[32:35], v[166:169], v[182:185], v[32:35]
	v_mfma_f32_16x16x32_bf16 v[20:23], v[144:147], v[206:209], v[20:23]
	v_mfma_f32_16x16x32_bf16 v[16:19], v[166:169], v[206:209], v[16:19]
	v_mfma_f32_16x16x32_bf16 v[4:7], v[144:147], v[214:217], v[4:7]
	v_mfma_f32_16x16x32_bf16 v[0:3], v[166:169], v[214:217], v[0:3]
	v_mfma_f32_16x16x32_bf16 v[52:55], v[162:165], v[178:181], v[52:55]
	v_mfma_f32_16x16x32_bf16 v[48:51], v[170:173], v[178:181], v[48:51]
	v_mfma_f32_16x16x32_bf16 v[36:39], v[162:165], v[194:197], v[36:39]
	v_mfma_f32_16x16x32_bf16 v[32:35], v[170:173], v[194:197], v[32:35]
	v_mfma_f32_16x16x32_bf16 v[20:23], v[162:165], v[210:213], v[20:23]
	v_mfma_f32_16x16x32_bf16 v[16:19], v[170:173], v[210:213], v[16:19]
	v_mfma_f32_16x16x32_bf16 v[4:7], v[162:165], v[218:221], v[4:7]
	v_mfma_f32_16x16x32_bf16 v[0:3], v[170:173], v[218:221], v[0:3]
	s_setprio 0
	s_barrier
	s_add_i32 s47, 0, 0x18000
	s_add_i32 s48, 0, 0x1c000
	v_add_u32_e32 v76, s47, v188
	v_add_u32_e32 v170, s48, v188
	ds_read_b128 v[56:59], v76
	ds_read_b128 v[60:63], v76 offset:1024
	ds_read_b128 v[68:71], v76 offset:2048
	ds_read_b128 v[76:79], v76 offset:3072
	ds_read_b128 v[144:147], v170
	ds_read_b128 v[162:165], v170 offset:1024
	ds_read_b128 v[166:169], v170 offset:2048
	ds_read_b128 v[170:173], v170 offset:3072
	s_add_u32 s22, s22, 0x100000
	s_addc_u32 s23, s23, 0
	s_mov_b32 m0, s31
	v_lshl_add_u64 v[226:227], s[22:23], 0, v[152:153]
	ds_read_b128 v[174:177], v189 offset:32768
	ds_read_b128 v[178:181], v189 offset:33792
	ds_read_b128 v[182:185], v189 offset:34816
	ds_read_b128 v[194:197], v189 offset:35840
	ds_read_b128 v[206:209], v189 offset:36864
	ds_read_b128 v[210:213], v189 offset:37888
	ds_read_b128 v[214:217], v189 offset:38912
	ds_read_b128 v[218:221], v189 offset:39936
	global_load_lds_dwordx4 v[226:227], off
	v_lshl_add_u64 v[226:227], s[22:23], 0, v[150:151]
	s_mov_b32 m0, s34
	s_nop 0
	global_load_lds_dwordx4 v[226:227], off
	s_waitcnt vmcnt(8)
	s_waitcnt lgkmcnt(0)
	s_barrier
	s_setprio 1
	s_waitcnt lgkmcnt(0)
	v_mfma_f32_16x16x32_bf16 v[64:67], v[56:59], v[174:177], v[64:67]
	v_mfma_f32_16x16x32_bf16 v[140:143], v[68:71], v[174:177], v[140:143]
	v_mfma_f32_16x16x32_bf16 v[128:131], v[56:59], v[182:185], v[128:131]
	v_mfma_f32_16x16x32_bf16 v[124:127], v[68:71], v[182:185], v[124:127]
	v_mfma_f32_16x16x32_bf16 v[112:115], v[56:59], v[206:209], v[112:115]
	v_mfma_f32_16x16x32_bf16 v[108:111], v[68:71], v[206:209], v[108:111]
	v_mfma_f32_16x16x32_bf16 v[96:99], v[56:59], v[214:217], v[96:99]
	v_mfma_f32_16x16x32_bf16 v[92:95], v[68:71], v[214:217], v[92:95]
	v_mfma_f32_16x16x32_bf16 v[64:67], v[60:63], v[178:181], v[64:67]
	v_mfma_f32_16x16x32_bf16 v[140:143], v[76:79], v[178:181], v[140:143]
	v_mfma_f32_16x16x32_bf16 v[128:131], v[60:63], v[194:197], v[128:131]
	v_mfma_f32_16x16x32_bf16 v[124:127], v[76:79], v[194:197], v[124:127]
	v_mfma_f32_16x16x32_bf16 v[112:115], v[60:63], v[210:213], v[112:115]
	v_mfma_f32_16x16x32_bf16 v[108:111], v[76:79], v[210:213], v[108:111]
	v_mfma_f32_16x16x32_bf16 v[96:99], v[60:63], v[218:221], v[96:99]
	v_mfma_f32_16x16x32_bf16 v[92:95], v[76:79], v[218:221], v[92:95]
	s_setprio 0
	s_setprio 1
	v_mfma_f32_16x16x32_bf16 v[136:139], v[144:147], v[174:177], v[136:139]
	v_mfma_f32_16x16x32_bf16 v[132:135], v[166:169], v[174:177], v[132:135]
	v_mfma_f32_16x16x32_bf16 v[120:123], v[144:147], v[182:185], v[120:123]
	v_mfma_f32_16x16x32_bf16 v[116:119], v[166:169], v[182:185], v[116:119]
	v_mfma_f32_16x16x32_bf16 v[104:107], v[144:147], v[206:209], v[104:107]
	v_mfma_f32_16x16x32_bf16 v[100:103], v[166:169], v[206:209], v[100:103]
	v_mfma_f32_16x16x32_bf16 v[88:91], v[144:147], v[214:217], v[88:91]
	v_mfma_f32_16x16x32_bf16 v[84:87], v[166:169], v[214:217], v[84:87]
	v_mfma_f32_16x16x32_bf16 v[136:139], v[162:165], v[178:181], v[136:139]
	v_mfma_f32_16x16x32_bf16 v[132:135], v[170:173], v[178:181], v[132:135]
	v_mfma_f32_16x16x32_bf16 v[120:123], v[162:165], v[194:197], v[120:123]
	v_mfma_f32_16x16x32_bf16 v[116:119], v[170:173], v[194:197], v[116:119]
	v_mfma_f32_16x16x32_bf16 v[104:107], v[162:165], v[210:213], v[104:107]
	v_mfma_f32_16x16x32_bf16 v[100:103], v[170:173], v[210:213], v[100:103]
	v_mfma_f32_16x16x32_bf16 v[88:91], v[162:165], v[218:221], v[88:91]
	v_mfma_f32_16x16x32_bf16 v[84:87], v[170:173], v[218:221], v[84:87]
	s_setprio 0
	s_barrier
; #define PG8_STAGE(bufoff, gbase, voff) do { _Pragma("unroll") for (int _i = 0; _i < 2; ++_i) \
;         __builtin_amdgcn_global_load_lds((const unsigned*)((const char*)(gbase) + (voff)[_i]), (PG8_LAS unsigned*)(lds + (bufoff) + ldsw + _i * 8192), 16, 0, 0); } while (0)
; #define PG8_LDA(dst, b, h) do { _Pragma("unroll") for (int m = 0; m < 4; ++m) _Pragma("unroll") for (int k = 0; k < 2; ++k) dst[m][k] = *(const PG8_LAS bf16x8*)(lds + PG8_SA(b, h) + aoff + m * 2048 + k * 1024); } while (0)
; #define PG8_MMA(ai, bj, At, Bt) do { __builtin_amdgcn_s_setprio(1); _Pragma("unroll") for (int m = 0; m < 4; ++m) _Pragma("unroll") for (int n = 0; n < 2; ++n) _Pragma("unroll") for (int k = 0; k < 2; ++k) \
;         acc[ai][bj][m][n] = __builtin_amdgcn_mfma_f32_16x16x32_bf16(Bt[n][k], At[m][k], acc[ai][bj][m][n], 0, 0, 0); __builtin_amdgcn_s_setprio(0); } while (0)
; #define PG8_WAIT_V(n) asm volatile("s_waitcnt vmcnt(" #n ")" ::: "memory")
; #define PG8_WAIT_L(n) asm volatile("s_waitcnt lgkmcnt(" #n ")" ::: "memory")
; #define PG8_BAR __builtin_amdgcn_s_barrier()
; #define PG8_SCHED __builtin_amdgcn_sched_barrier(0)
; template <class Epi, class Sched, bool ALIGN_EPI = false, bool SP2 = false>
; __device__ __forceinline__ void gemm_phase(PG8_LAS unsigned char* lds, const Gemm g, const Sched& S, const Epi& E) {
;     ...
;         for (int t = 0; t < nt; t += 2) {
;             const bool last = (t == nt - 2);
;             const char* a1 = cA + (size_t)(t + 1) * kstep;
;             const char* a2 = last ? nA : cA + (size_t)(t + 2) * kstep; const char* b2 = last ? nB : cB + (size_t)(t + 2) * kstep;
;     ...
;             PG8_LDA(At, 1, 1); PG8_STAGE(PG8_SB(1, 0), b3, voffB); PG8_STAGE(PG8_SB(1, 1), b3 + hstep, voffB); PG8_STAGE(PG8_SA(1, 0), a3, voffA);
;             PG8_WAIT_V(8); PG8_WAIT_L(0); PG8_BAR; PG8_MMA(1, 0, At, B0); PG8_MMA(1, 1, At, B1); PG8_BAR; PG8_SCHED;
	s_add_i32 s22, s47, s28
	v_lshl_add_u64 v[158:159], v[158:159], 0, s[38:39]
	s_mov_b32 m0, s22
	ds_read_b128 v[174:177], v189 offset:49152
	ds_read_b128 v[178:181], v189 offset:50176
	ds_read_b128 v[182:185], v189 offset:51200
	ds_read_b128 v[194:197], v189 offset:52224
	ds_read_b128 v[206:209], v189 offset:53248
	ds_read_b128 v[210:213], v189 offset:54272
	ds_read_b128 v[214:217], v189 offset:55296
	ds_read_b128 v[218:221], v189 offset:56320
	global_load_lds_dwordx4 v[158:159], off
	s_add_i32 m0, s22, 0x2000
	s_add_u32 s4, s4, 0x100080
	v_lshl_add_u64 v[158:159], v[186:187], 0, s[38:39]
	s_addc_u32 s5, s5, 0
	s_add_i32 s22, s48, s28
	global_load_lds_dwordx4 v[158:159], off
	v_lshl_add_u64 v[158:159], s[4:5], 0, v[160:161]
	s_mov_b32 m0, s22
	s_nop 0
	global_load_lds_dwordx4 v[158:159], off
	v_lshl_add_u64 v[158:159], s[4:5], 0, v[148:149]
	s_add_i32 m0, s22, 0x2000
	s_nop 0
	global_load_lds_dwordx4 v[158:159], off
	v_lshl_add_u64 v[158:159], v[222:223], 0, s[38:39]
	s_mov_b32 m0, s37
	s_nop 0
	global_load_lds_dwordx4 v[158:159], off
	v_lshl_add_u64 v[158:159], v[224:225], 0, s[38:39]
	s_mov_b32 m0, s40
	s_nop 0
	global_load_lds_dwordx4 v[158:159], off
	s_waitcnt vmcnt(8)
	s_waitcnt lgkmcnt(0)
	s_barrier
	s_setprio 1
	s_waitcnt lgkmcnt(0)
	v_mfma_f32_16x16x32_bf16 v[80:83], v[56:59], v[174:177], v[80:83]
	v_mfma_f32_16x16x32_bf16 v[72:75], v[68:71], v[174:177], v[72:75]
	v_mfma_f32_16x16x32_bf16 v[44:47], v[56:59], v[182:185], v[44:47]
	v_mfma_f32_16x16x32_bf16 v[40:43], v[68:71], v[182:185], v[40:43]
	v_mfma_f32_16x16x32_bf16 v[28:31], v[56:59], v[206:209], v[28:31]
	v_mfma_f32_16x16x32_bf16 v[24:27], v[68:71], v[206:209], v[24:27]
	v_mfma_f32_16x16x32_bf16 v[12:15], v[56:59], v[214:217], v[12:15]
	v_mfma_f32_16x16x32_bf16 v[8:11], v[68:71], v[214:217], v[8:11]
	v_mfma_f32_16x16x32_bf16 v[80:83], v[60:63], v[178:181], v[80:83]
	v_mfma_f32_16x16x32_bf16 v[72:75], v[76:79], v[178:181], v[72:75]
	v_mfma_f32_16x16x32_bf16 v[44:47], v[60:63], v[194:197], v[44:47]
	v_mfma_f32_16x16x32_bf16 v[40:43], v[76:79], v[194:197], v[40:43]
	v_mfma_f32_16x16x32_bf16 v[28:31], v[60:63], v[210:213], v[28:31]
	v_mfma_f32_16x16x32_bf16 v[24:27], v[76:79], v[210:213], v[24:27]
	v_mfma_f32_16x16x32_bf16 v[12:15], v[60:63], v[218:221], v[12:15]
	v_mfma_f32_16x16x32_bf16 v[8:11], v[76:79], v[218:221], v[8:11]
	s_setprio 0
	s_setprio 1
	v_mfma_f32_16x16x32_bf16 v[52:55], v[144:147], v[174:177], v[52:55]
	v_mfma_f32_16x16x32_bf16 v[48:51], v[166:169], v[174:177], v[48:51]
	v_mfma_f32_16x16x32_bf16 v[36:39], v[144:147], v[182:185], v[36:39]
	v_mfma_f32_16x16x32_bf16 v[32:35], v[166:169], v[182:185], v[32:35]
	v_mfma_f32_16x16x32_bf16 v[20:23], v[144:147], v[206:209], v[20:23]
	v_mfma_f32_16x16x32_bf16 v[16:19], v[166:169], v[206:209], v[16:19]
	v_mfma_f32_16x16x32_bf16 v[4:7], v[144:147], v[214:217], v[4:7]
	v_mfma_f32_16x16x32_bf16 v[0:3], v[166:169], v[214:217], v[0:3]
	v_mfma_f32_16x16x32_bf16 v[52:55], v[162:165], v[178:181], v[52:55]
	v_mfma_f32_16x16x32_bf16 v[48:51], v[170:173], v[178:181], v[48:51]
	v_mfma_f32_16x16x32_bf16 v[36:39], v[162:165], v[194:197], v[36:39]
	v_mfma_f32_16x16x32_bf16 v[32:35], v[170:173], v[194:197], v[32:35]
	v_mfma_f32_16x16x32_bf16 v[20:23], v[162:165], v[210:213], v[20:23]
	v_mfma_f32_16x16x32_bf16 v[16:19], v[170:173], v[210:213], v[16:19]
	v_mfma_f32_16x16x32_bf16 v[4:7], v[162:165], v[218:221], v[4:7]
	v_mfma_f32_16x16x32_bf16 v[0:3], v[170:173], v[218:221], v[0:3]
	s_setprio 0
	s_add_i32 s46, s46, 2
	s_add_u32 s2, s2, 0x100
	s_addc_u32 s3, s3, 0
	s_add_u32 s44, s44, 0x100
	s_addc_u32 s45, s45, 0
	s_add_u32 s4, s2, 0xfff00080
	s_addc_u32 s5, s3, -1
	s_add_i32 s47, 0, 0x10000
	s_cmp_eq_u32 s46, 60
	s_cselect_b32 s23, s15, s5
	s_cselect_b32 s22, s42, s4
	s_cselect_b32 s5, s17, s45
	s_cselect_b32 s4, s43, s44
	s_add_i32 s50, 0, 0x14000
	s_cmp_gt_u32 s46, 61
	s_barrier
	s_cbranch_scc0 .Lkrot_1215
	s_and_b64 vcc, exec, s[10:11]
	s_cbranch_vccz .LBB0_1218
	s_barrier
